# v107: v99 with streaming (nt) x_new stores in the folded residual epilogues
# baseline (speedup 1.0000x reference)
.Lrf_bar:
	s_barrier
	global_load_dwordx4 v[200:203], v253, s[10:11] offset:0
	global_load_dwordx4 v[204:207], v253, s[10:11] offset:256
	global_load_dwordx4 v[208:211], v253, s[10:11] offset:512
	global_load_dwordx4 v[212:215], v253, s[10:11] offset:768
	global_load_dwordx4 v[216:219], v253, s[10:11] offset:2048
	global_load_dwordx4 v[220:223], v253, s[10:11] offset:2304
	global_load_dwordx4 v[240:243], v253, s[10:11] offset:2560
	global_load_dwordx4 v[244:247], v253, s[10:11] offset:2816
	v_lshl_add_u32 v251, v236, 2, s68
	v_lshlrev_b32_e32 v251, 1, v251
	v_add_u32_e32 v249, s67, v235
	v_mul_u32_u24_e32 v249, 0x210, v249
	v_add_u32_e32 v251, v251, v249
	v_add_u32_e32 v252, 0x10800, v251
	s_mov_b32 s2, 0x3a800000
	s_waitcnt vmcnt(7)
	v_add_f32_e32 v200, v200, v201
	v_add_f32_e32 v202, v202, v203
	v_add_f32_e32 v200, v200, v202
	v_fma_f32 v200, v200, s2, v167
	v_rsq_f32_e32 v200, v200
	s_waitcnt vmcnt(6)
	v_add_f32_e32 v204, v204, v205
	v_add_f32_e32 v206, v206, v207
	v_add_f32_e32 v204, v204, v206
	v_fma_f32 v204, v204, s2, v167
	v_rsq_f32_e32 v204, v204
	s_waitcnt vmcnt(5)
	v_add_f32_e32 v208, v208, v209
	v_add_f32_e32 v210, v210, v211
	v_add_f32_e32 v208, v208, v210
	v_fma_f32 v208, v208, s2, v167
	v_rsq_f32_e32 v208, v208
	s_waitcnt vmcnt(4)
	v_add_f32_e32 v212, v212, v213
	v_add_f32_e32 v214, v214, v215
	v_add_f32_e32 v212, v212, v214
	v_fma_f32 v212, v212, s2, v167
	v_rsq_f32_e32 v212, v212
	s_waitcnt vmcnt(3)
	v_add_f32_e32 v216, v216, v217
	v_add_f32_e32 v218, v218, v219
	v_add_f32_e32 v216, v216, v218
	v_fma_f32 v216, v216, s2, v167
	v_rsq_f32_e32 v216, v216
	s_waitcnt vmcnt(2)
	v_add_f32_e32 v220, v220, v221
	v_add_f32_e32 v222, v222, v223
	v_add_f32_e32 v220, v220, v222
	v_fma_f32 v220, v220, s2, v167
	v_rsq_f32_e32 v220, v220
	s_waitcnt vmcnt(1)
	v_add_f32_e32 v240, v240, v241
	v_add_f32_e32 v242, v242, v243
	v_add_f32_e32 v240, v240, v242
	v_fma_f32 v240, v240, s2, v167
	v_rsq_f32_e32 v240, v240
	s_waitcnt vmcnt(0)
	v_add_f32_e32 v244, v244, v245
	v_add_f32_e32 v246, v246, v247
	v_add_f32_e32 v244, v244, v246
	v_fma_f32 v244, v244, s2, v167
	v_rsq_f32_e32 v244, v244
	s_nop 0
	v_readlane_b32 s8, v254, 61
	s_cmp_eq_u32 s8, 34
	s_cbranch_scc1 .Lrf_fin2
	global_store_dwordx4 v248, v[126:129], s[100:101] offset:0 nt
	global_store_dwordx4 v248, v[122:125], s[100:101] offset:64 nt
	global_store_dwordx4 v248, v[118:121], s[100:101] offset:512 nt
	global_store_dwordx4 v248, v[114:117], s[100:101] offset:576 nt
	s_nop 1
	v_mul_f32_e32 v126, v126, v200
	v_mul_f32_e32 v127, v127, v200
	v_mul_f32_e32 v128, v128, v200
	v_mul_f32_e32 v129, v129, v200
	v_fma_f32 v126, v126, v146, v162
	v_fma_f32 v127, v127, v147, v163
	v_fma_f32 v128, v128, v148, v164
	v_fma_f32 v129, v129, v149, v165
	v_cvt_pk_bf16_f32 v126, v126, v127
	v_cvt_pk_bf16_f32 v127, v128, v129
	v_mul_f32_e32 v122, v122, v200
	v_mul_f32_e32 v123, v123, v200
	v_mul_f32_e32 v124, v124, v200
	v_mul_f32_e32 v125, v125, v200
	v_fma_f32 v122, v122, v150, v188
	v_fma_f32 v123, v123, v151, v189
	v_fma_f32 v124, v124, v152, v190
	v_fma_f32 v125, v125, v153, v191
	v_cvt_pk_bf16_f32 v122, v122, v123
	v_cvt_pk_bf16_f32 v123, v124, v125
	v_mul_f32_e32 v118, v118, v200
	v_mul_f32_e32 v119, v119, v200
	v_mul_f32_e32 v120, v120, v200
	v_mul_f32_e32 v121, v121, v200
	v_fma_f32 v118, v118, v154, v192
	v_fma_f32 v119, v119, v155, v193
	v_fma_f32 v120, v120, v156, v194
	v_fma_f32 v121, v121, v157, v195
	v_cvt_pk_bf16_f32 v118, v118, v119
	v_cvt_pk_bf16_f32 v119, v120, v121
	v_mul_f32_e32 v114, v114, v200
	v_mul_f32_e32 v115, v115, v200
	v_mul_f32_e32 v116, v116, v200
	v_mul_f32_e32 v117, v117, v200
	v_fma_f32 v114, v114, v158, v196
	v_fma_f32 v115, v115, v159, v197
	v_fma_f32 v116, v116, v160, v198
	v_fma_f32 v117, v117, v161, v199
	v_cvt_pk_bf16_f32 v114, v114, v115
	v_cvt_pk_bf16_f32 v115, v116, v117
	ds_write_b64 v251, v[126:127] offset:0
	ds_write_b64 v251, v[122:123] offset:32
	ds_write_b64 v251, v[118:119] offset:256
	ds_write_b64 v251, v[114:115] offset:288
	s_add_u32 s8, s100, 0x10000
	s_addc_u32 s9, s101, 0
	global_store_dwordx4 v248, v[110:113], s[8:9] offset:0 nt
	global_store_dwordx4 v248, v[106:109], s[8:9] offset:64 nt
	global_store_dwordx4 v248, v[102:105], s[8:9] offset:512 nt
	global_store_dwordx4 v248, v[98:101], s[8:9] offset:576 nt
	s_nop 1
	v_mul_f32_e32 v110, v110, v204
	v_mul_f32_e32 v111, v111, v204
	v_mul_f32_e32 v112, v112, v204
	v_mul_f32_e32 v113, v113, v204
	v_fma_f32 v110, v110, v146, v162
	v_fma_f32 v111, v111, v147, v163
	v_fma_f32 v112, v112, v148, v164
	v_fma_f32 v113, v113, v149, v165
	v_cvt_pk_bf16_f32 v110, v110, v111
	v_cvt_pk_bf16_f32 v111, v112, v113
	v_mul_f32_e32 v106, v106, v204
	v_mul_f32_e32 v107, v107, v204
	v_mul_f32_e32 v108, v108, v204
	v_mul_f32_e32 v109, v109, v204
	v_fma_f32 v106, v106, v150, v188
	v_fma_f32 v107, v107, v151, v189
	v_fma_f32 v108, v108, v152, v190
	v_fma_f32 v109, v109, v153, v191
	v_cvt_pk_bf16_f32 v106, v106, v107
	v_cvt_pk_bf16_f32 v107, v108, v109
	v_mul_f32_e32 v102, v102, v204
	v_mul_f32_e32 v103, v103, v204
	v_mul_f32_e32 v104, v104, v204
	v_mul_f32_e32 v105, v105, v204
	v_fma_f32 v102, v102, v154, v192
	v_fma_f32 v103, v103, v155, v193
	v_fma_f32 v104, v104, v156, v194
	v_fma_f32 v105, v105, v157, v195
	v_cvt_pk_bf16_f32 v102, v102, v103
	v_cvt_pk_bf16_f32 v103, v104, v105
	v_mul_f32_e32 v98, v98, v204
	v_mul_f32_e32 v99, v99, v204
	v_mul_f32_e32 v100, v100, v204
	v_mul_f32_e32 v101, v101, v204
	v_fma_f32 v98, v98, v158, v196
	v_fma_f32 v99, v99, v159, v197
	v_fma_f32 v100, v100, v160, v198
	v_fma_f32 v101, v101, v161, v199
	v_cvt_pk_bf16_f32 v98, v98, v99
	v_cvt_pk_bf16_f32 v99, v100, v101
	ds_write_b64 v251, v[110:111] offset:8448
	ds_write_b64 v251, v[106:107] offset:8480
	ds_write_b64 v251, v[102:103] offset:8704
	ds_write_b64 v251, v[98:99] offset:8736
	s_add_u32 s8, s100, 0x20000
	s_addc_u32 s9, s101, 0
	global_store_dwordx4 v248, v[94:97], s[8:9] offset:0 nt
	global_store_dwordx4 v248, v[90:93], s[8:9] offset:64 nt
	global_store_dwordx4 v248, v[86:89], s[8:9] offset:512 nt
	global_store_dwordx4 v248, v[82:85], s[8:9] offset:576 nt
	s_nop 1
	v_mul_f32_e32 v94, v94, v208
	v_mul_f32_e32 v95, v95, v208
	v_mul_f32_e32 v96, v96, v208
	v_mul_f32_e32 v97, v97, v208
	v_fma_f32 v94, v94, v146, v162
	v_fma_f32 v95, v95, v147, v163
	v_fma_f32 v96, v96, v148, v164
	v_fma_f32 v97, v97, v149, v165
	v_cvt_pk_bf16_f32 v94, v94, v95
	v_cvt_pk_bf16_f32 v95, v96, v97
	v_mul_f32_e32 v90, v90, v208
	v_mul_f32_e32 v91, v91, v208
	v_mul_f32_e32 v92, v92, v208
	v_mul_f32_e32 v93, v93, v208
	v_fma_f32 v90, v90, v150, v188
	v_fma_f32 v91, v91, v151, v189
	v_fma_f32 v92, v92, v152, v190
	v_fma_f32 v93, v93, v153, v191
	v_cvt_pk_bf16_f32 v90, v90, v91
	v_cvt_pk_bf16_f32 v91, v92, v93
	v_mul_f32_e32 v86, v86, v208
	v_mul_f32_e32 v87, v87, v208
	v_mul_f32_e32 v88, v88, v208
	v_mul_f32_e32 v89, v89, v208
	v_fma_f32 v86, v86, v154, v192
	v_fma_f32 v87, v87, v155, v193
	v_fma_f32 v88, v88, v156, v194
	v_fma_f32 v89, v89, v157, v195
	v_cvt_pk_bf16_f32 v86, v86, v87
	v_cvt_pk_bf16_f32 v87, v88, v89
	v_mul_f32_e32 v82, v82, v208
	v_mul_f32_e32 v83, v83, v208
	v_mul_f32_e32 v84, v84, v208
	v_mul_f32_e32 v85, v85, v208
	v_fma_f32 v82, v82, v158, v196
	v_fma_f32 v83, v83, v159, v197
	v_fma_f32 v84, v84, v160, v198
	v_fma_f32 v85, v85, v161, v199
	v_cvt_pk_bf16_f32 v82, v82, v83
	v_cvt_pk_bf16_f32 v83, v84, v85
	ds_write_b64 v251, v[94:95] offset:16896
	ds_write_b64 v251, v[90:91] offset:16928
	ds_write_b64 v251, v[86:87] offset:17152
	ds_write_b64 v251, v[82:83] offset:17184
	s_add_u32 s8, s100, 0x30000
	s_addc_u32 s9, s101, 0
	global_store_dwordx4 v248, v[78:81], s[8:9] offset:0 nt
	global_store_dwordx4 v248, v[74:77], s[8:9] offset:64 nt
	global_store_dwordx4 v248, v[70:73], s[8:9] offset:512 nt
	global_store_dwordx4 v248, v[66:69], s[8:9] offset:576 nt
	s_nop 1
	v_mul_f32_e32 v78, v78, v212
	v_mul_f32_e32 v79, v79, v212
	v_mul_f32_e32 v80, v80, v212
	v_mul_f32_e32 v81, v81, v212
	v_fma_f32 v78, v78, v146, v162
	v_fma_f32 v79, v79, v147, v163
	v_fma_f32 v80, v80, v148, v164
	v_fma_f32 v81, v81, v149, v165
	v_cvt_pk_bf16_f32 v78, v78, v79
	v_cvt_pk_bf16_f32 v79, v80, v81
	v_mul_f32_e32 v74, v74, v212
	v_mul_f32_e32 v75, v75, v212
	v_mul_f32_e32 v76, v76, v212
	v_mul_f32_e32 v77, v77, v212
	v_fma_f32 v74, v74, v150, v188
	v_fma_f32 v75, v75, v151, v189
	v_fma_f32 v76, v76, v152, v190
	v_fma_f32 v77, v77, v153, v191
	v_cvt_pk_bf16_f32 v74, v74, v75
	v_cvt_pk_bf16_f32 v75, v76, v77
	v_mul_f32_e32 v70, v70, v212
	v_mul_f32_e32 v71, v71, v212
	v_mul_f32_e32 v72, v72, v212
	v_mul_f32_e32 v73, v73, v212
	v_fma_f32 v70, v70, v154, v192
	v_fma_f32 v71, v71, v155, v193
	v_fma_f32 v72, v72, v156, v194
	v_fma_f32 v73, v73, v157, v195
	v_cvt_pk_bf16_f32 v70, v70, v71
	v_cvt_pk_bf16_f32 v71, v72, v73
	v_mul_f32_e32 v66, v66, v212
	v_mul_f32_e32 v67, v67, v212
	v_mul_f32_e32 v68, v68, v212
	v_mul_f32_e32 v69, v69, v212
	v_fma_f32 v66, v66, v158, v196
	v_fma_f32 v67, v67, v159, v197
	v_fma_f32 v68, v68, v160, v198
	v_fma_f32 v69, v69, v161, v199
	v_cvt_pk_bf16_f32 v66, v66, v67
	v_cvt_pk_bf16_f32 v67, v68, v69
	ds_write_b64 v251, v[78:79] offset:25344
	ds_write_b64 v251, v[74:75] offset:25376
	ds_write_b64 v251, v[70:71] offset:25600
	ds_write_b64 v251, v[66:67] offset:25632
	s_add_u32 s8, s100, 0x80000
	s_addc_u32 s9, s101, 0
	global_store_dwordx4 v248, v[62:65], s[8:9] offset:0 nt
	global_store_dwordx4 v248, v[58:61], s[8:9] offset:64 nt
	global_store_dwordx4 v248, v[54:57], s[8:9] offset:512 nt
	global_store_dwordx4 v248, v[50:53], s[8:9] offset:576 nt
	s_nop 1
	v_mul_f32_e32 v62, v62, v216
	v_mul_f32_e32 v63, v63, v216
	v_mul_f32_e32 v64, v64, v216
	v_mul_f32_e32 v65, v65, v216
	v_fma_f32 v62, v62, v146, v162
	v_fma_f32 v63, v63, v147, v163
	v_fma_f32 v64, v64, v148, v164
	v_fma_f32 v65, v65, v149, v165
	v_cvt_pk_bf16_f32 v62, v62, v63
	v_cvt_pk_bf16_f32 v63, v64, v65
	v_mul_f32_e32 v58, v58, v216
	v_mul_f32_e32 v59, v59, v216
	v_mul_f32_e32 v60, v60, v216
	v_mul_f32_e32 v61, v61, v216
	v_fma_f32 v58, v58, v150, v188
	v_fma_f32 v59, v59, v151, v189
	v_fma_f32 v60, v60, v152, v190
	v_fma_f32 v61, v61, v153, v191
	v_cvt_pk_bf16_f32 v58, v58, v59
	v_cvt_pk_bf16_f32 v59, v60, v61
	v_mul_f32_e32 v54, v54, v216
	v_mul_f32_e32 v55, v55, v216
	v_mul_f32_e32 v56, v56, v216
	v_mul_f32_e32 v57, v57, v216
	v_fma_f32 v54, v54, v154, v192
	v_fma_f32 v55, v55, v155, v193
	v_fma_f32 v56, v56, v156, v194
	v_fma_f32 v57, v57, v157, v195
	v_cvt_pk_bf16_f32 v54, v54, v55
	v_cvt_pk_bf16_f32 v55, v56, v57
	v_mul_f32_e32 v50, v50, v216
	v_mul_f32_e32 v51, v51, v216
	v_mul_f32_e32 v52, v52, v216
	v_mul_f32_e32 v53, v53, v216
	v_fma_f32 v50, v50, v158, v196
	v_fma_f32 v51, v51, v159, v197
	v_fma_f32 v52, v52, v160, v198
	v_fma_f32 v53, v53, v161, v199
	v_cvt_pk_bf16_f32 v50, v50, v51
	v_cvt_pk_bf16_f32 v51, v52, v53
	ds_write_b64 v252, v[62:63] offset:0
	ds_write_b64 v252, v[58:59] offset:32
	ds_write_b64 v252, v[54:55] offset:256
	ds_write_b64 v252, v[50:51] offset:288
	s_add_u32 s8, s100, 0x90000
	s_addc_u32 s9, s101, 0
	global_store_dwordx4 v248, v[46:49], s[8:9] offset:0 nt
	global_store_dwordx4 v248, v[42:45], s[8:9] offset:64 nt
	global_store_dwordx4 v248, v[38:41], s[8:9] offset:512 nt
	global_store_dwordx4 v248, v[34:37], s[8:9] offset:576 nt
	s_nop 1
	v_mul_f32_e32 v46, v46, v220
	v_mul_f32_e32 v47, v47, v220
	v_mul_f32_e32 v48, v48, v220
	v_mul_f32_e32 v49, v49, v220
	v_fma_f32 v46, v46, v146, v162
	v_fma_f32 v47, v47, v147, v163
	v_fma_f32 v48, v48, v148, v164
	v_fma_f32 v49, v49, v149, v165
	v_cvt_pk_bf16_f32 v46, v46, v47
	v_cvt_pk_bf16_f32 v47, v48, v49
	v_mul_f32_e32 v42, v42, v220
	v_mul_f32_e32 v43, v43, v220
	v_mul_f32_e32 v44, v44, v220
	v_mul_f32_e32 v45, v45, v220
	v_fma_f32 v42, v42, v150, v188
	v_fma_f32 v43, v43, v151, v189
	v_fma_f32 v44, v44, v152, v190
	v_fma_f32 v45, v45, v153, v191
	v_cvt_pk_bf16_f32 v42, v42, v43
	v_cvt_pk_bf16_f32 v43, v44, v45
	v_mul_f32_e32 v38, v38, v220
	v_mul_f32_e32 v39, v39, v220
	v_mul_f32_e32 v40, v40, v220
	v_mul_f32_e32 v41, v41, v220
	v_fma_f32 v38, v38, v154, v192
	v_fma_f32 v39, v39, v155, v193
	v_fma_f32 v40, v40, v156, v194
	v_fma_f32 v41, v41, v157, v195
	v_cvt_pk_bf16_f32 v38, v38, v39
	v_cvt_pk_bf16_f32 v39, v40, v41
	v_mul_f32_e32 v34, v34, v220
	v_mul_f32_e32 v35, v35, v220
	v_mul_f32_e32 v36, v36, v220
	v_mul_f32_e32 v37, v37, v220
	v_fma_f32 v34, v34, v158, v196
	v_fma_f32 v35, v35, v159, v197
	v_fma_f32 v36, v36, v160, v198
	v_fma_f32 v37, v37, v161, v199
	v_cvt_pk_bf16_f32 v34, v34, v35
	v_cvt_pk_bf16_f32 v35, v36, v37
	ds_write_b64 v252, v[46:47] offset:8448
	ds_write_b64 v252, v[42:43] offset:8480
	ds_write_b64 v252, v[38:39] offset:8704
	ds_write_b64 v252, v[34:35] offset:8736
	s_add_u32 s8, s100, 0xa0000
	s_addc_u32 s9, s101, 0
	global_store_dwordx4 v248, v[30:33], s[8:9] offset:0 nt
	global_store_dwordx4 v248, v[26:29], s[8:9] offset:64 nt
	global_store_dwordx4 v248, v[22:25], s[8:9] offset:512 nt
	global_store_dwordx4 v248, v[18:21], s[8:9] offset:576 nt
	s_nop 1
	v_mul_f32_e32 v30, v30, v240
	v_mul_f32_e32 v31, v31, v240
	v_mul_f32_e32 v32, v32, v240
	v_mul_f32_e32 v33, v33, v240
	v_fma_f32 v30, v30, v146, v162
	v_fma_f32 v31, v31, v147, v163
	v_fma_f32 v32, v32, v148, v164
	v_fma_f32 v33, v33, v149, v165
	v_cvt_pk_bf16_f32 v30, v30, v31
	v_cvt_pk_bf16_f32 v31, v32, v33
	v_mul_f32_e32 v26, v26, v240
	v_mul_f32_e32 v27, v27, v240
	v_mul_f32_e32 v28, v28, v240
	v_mul_f32_e32 v29, v29, v240
	v_fma_f32 v26, v26, v150, v188
	v_fma_f32 v27, v27, v151, v189
	v_fma_f32 v28, v28, v152, v190
	v_fma_f32 v29, v29, v153, v191
	v_cvt_pk_bf16_f32 v26, v26, v27
	v_cvt_pk_bf16_f32 v27, v28, v29
	v_mul_f32_e32 v22, v22, v240
	v_mul_f32_e32 v23, v23, v240
	v_mul_f32_e32 v24, v24, v240
	v_mul_f32_e32 v25, v25, v240
	v_fma_f32 v22, v22, v154, v192
	v_fma_f32 v23, v23, v155, v193
	v_fma_f32 v24, v24, v156, v194
	v_fma_f32 v25, v25, v157, v195
	v_cvt_pk_bf16_f32 v22, v22, v23
	v_cvt_pk_bf16_f32 v23, v24, v25
	v_mul_f32_e32 v18, v18, v240
	v_mul_f32_e32 v19, v19, v240
	v_mul_f32_e32 v20, v20, v240
	v_mul_f32_e32 v21, v21, v240
	v_fma_f32 v18, v18, v158, v196
	v_fma_f32 v19, v19, v159, v197
	v_fma_f32 v20, v20, v160, v198
	v_fma_f32 v21, v21, v161, v199
	v_cvt_pk_bf16_f32 v18, v18, v19
	v_cvt_pk_bf16_f32 v19, v20, v21
	ds_write_b64 v252, v[30:31] offset:16896
	ds_write_b64 v252, v[26:27] offset:16928
	ds_write_b64 v252, v[22:23] offset:17152
	ds_write_b64 v252, v[18:19] offset:17184
	s_add_u32 s8, s100, 0xb0000
	s_addc_u32 s9, s101, 0
	global_store_dwordx4 v248, v[14:17], s[8:9] offset:0 nt
	global_store_dwordx4 v248, v[10:13], s[8:9] offset:64 nt
	global_store_dwordx4 v248, v[6:9], s[8:9] offset:512 nt
	global_store_dwordx4 v248, v[2:5], s[8:9] offset:576 nt
	s_nop 1
	v_mul_f32_e32 v14, v14, v244
	v_mul_f32_e32 v15, v15, v244
	v_mul_f32_e32 v16, v16, v244
	v_mul_f32_e32 v17, v17, v244
	v_fma_f32 v14, v14, v146, v162
	v_fma_f32 v15, v15, v147, v163
	v_fma_f32 v16, v16, v148, v164
	v_fma_f32 v17, v17, v149, v165
	v_cvt_pk_bf16_f32 v14, v14, v15
	v_cvt_pk_bf16_f32 v15, v16, v17
	v_mul_f32_e32 v10, v10, v244
	v_mul_f32_e32 v11, v11, v244
	v_mul_f32_e32 v12, v12, v244
	v_mul_f32_e32 v13, v13, v244
	v_fma_f32 v10, v10, v150, v188
	v_fma_f32 v11, v11, v151, v189
	v_fma_f32 v12, v12, v152, v190
	v_fma_f32 v13, v13, v153, v191
	v_cvt_pk_bf16_f32 v10, v10, v11
	v_cvt_pk_bf16_f32 v11, v12, v13
	v_mul_f32_e32 v6, v6, v244
	v_mul_f32_e32 v7, v7, v244
	v_mul_f32_e32 v8, v8, v244
	v_mul_f32_e32 v9, v9, v244
	v_fma_f32 v6, v6, v154, v192
	v_fma_f32 v7, v7, v155, v193
	v_fma_f32 v8, v8, v156, v194
	v_fma_f32 v9, v9, v157, v195
	v_cvt_pk_bf16_f32 v6, v6, v7
	v_cvt_pk_bf16_f32 v7, v8, v9
	v_mul_f32_e32 v2, v2, v244
	v_mul_f32_e32 v3, v3, v244
	v_mul_f32_e32 v4, v4, v244
	v_mul_f32_e32 v5, v5, v244
	v_fma_f32 v2, v2, v158, v196
	v_fma_f32 v3, v3, v159, v197
	v_fma_f32 v4, v4, v160, v198
	v_fma_f32 v5, v5, v161, v199
	v_cvt_pk_bf16_f32 v2, v2, v3
	v_cvt_pk_bf16_f32 v3, v4, v5
	ds_write_b64 v252, v[14:15] offset:25344
	ds_write_b64 v252, v[10:11] offset:25376
	ds_write_b64 v252, v[6:7] offset:25600
	ds_write_b64 v252, v[2:3] offset:25632
	v_lshl_add_u32 v249, v236, 4, v235
	v_lshrrev_b32_e32 v250, 5, v249
	v_and_b32_e32 v249, 31, v249
	v_lshlrev_b32_e32 v249, 4, v249
	v_lshl_add_u32 v250, s3, 5, v250
	v_mul_u32_u24_e32 v251, 0x210, v250
	v_add_u32_e32 v251, v251, v249
	v_lshl_add_u32 v248, v250, 11, v249
	v_readlane_b32 s12, v255, 9
	v_readlane_b32 s13, v255, 10
	s_lshl_b32 s2, s17, 19
	s_lshl_b32 s8, s48, 9
	s_add_i32 s2, s2, s8
	s_add_u32 s12, s12, s2
	s_addc_u32 s13, s13, 0
	s_waitcnt lgkmcnt(0)
	s_barrier
	ds_read_b128 v[2:5], v251 offset:0
	ds_read_b128 v[6:9], v251 offset:1056
	ds_read_b128 v[10:13], v251 offset:2112
	ds_read_b128 v[14:17], v251 offset:3168
	ds_read_b128 v[18:21], v251 offset:4224
	ds_read_b128 v[22:25], v251 offset:5280
	ds_read_b128 v[26:29], v251 offset:6336
	ds_read_b128 v[30:33], v251 offset:7392
	ds_read_b128 v[34:37], v251 offset:8448
	ds_read_b128 v[38:41], v251 offset:9504
	ds_read_b128 v[42:45], v251 offset:10560
	ds_read_b128 v[46:49], v251 offset:11616
	ds_read_b128 v[50:53], v251 offset:12672
	ds_read_b128 v[54:57], v251 offset:13728
	ds_read_b128 v[58:61], v251 offset:14784
	ds_read_b128 v[62:65], v251 offset:15840
	s_waitcnt lgkmcnt(15)
	global_store_dwordx4 v248, v[2:5], s[12:13]
	s_waitcnt lgkmcnt(14)
	s_add_u32 s14, s12, 0x1000
	s_addc_u32 s15, s13, 0
	global_store_dwordx4 v248, v[6:9], s[14:15]
	s_waitcnt lgkmcnt(13)
	s_add_u32 s14, s12, 0x2000
	s_addc_u32 s15, s13, 0
	global_store_dwordx4 v248, v[10:13], s[14:15]
	s_waitcnt lgkmcnt(12)
	s_add_u32 s14, s12, 0x3000
	s_addc_u32 s15, s13, 0
	global_store_dwordx4 v248, v[14:17], s[14:15]
	s_waitcnt lgkmcnt(11)
	s_add_u32 s14, s12, 0x4000
	s_addc_u32 s15, s13, 0
	global_store_dwordx4 v248, v[18:21], s[14:15]
	s_waitcnt lgkmcnt(10)
	s_add_u32 s14, s12, 0x5000
	s_addc_u32 s15, s13, 0
	global_store_dwordx4 v248, v[22:25], s[14:15]
	s_waitcnt lgkmcnt(9)
	s_add_u32 s14, s12, 0x6000
	s_addc_u32 s15, s13, 0
	global_store_dwordx4 v248, v[26:29], s[14:15]
	s_waitcnt lgkmcnt(8)
	s_add_u32 s14, s12, 0x7000
	s_addc_u32 s15, s13, 0
	global_store_dwordx4 v248, v[30:33], s[14:15]
	s_waitcnt lgkmcnt(7)
	s_add_u32 s14, s12, 0x8000
	s_addc_u32 s15, s13, 0
	global_store_dwordx4 v248, v[34:37], s[14:15]
	s_waitcnt lgkmcnt(6)
	s_add_u32 s14, s12, 0x9000
	s_addc_u32 s15, s13, 0
	global_store_dwordx4 v248, v[38:41], s[14:15]
	s_waitcnt lgkmcnt(5)
	s_add_u32 s14, s12, 0xa000
	s_addc_u32 s15, s13, 0
	global_store_dwordx4 v248, v[42:45], s[14:15]
	s_waitcnt lgkmcnt(4)
	s_add_u32 s14, s12, 0xb000
	s_addc_u32 s15, s13, 0
	global_store_dwordx4 v248, v[46:49], s[14:15]
	s_waitcnt lgkmcnt(3)
	s_add_u32 s14, s12, 0xc000
	s_addc_u32 s15, s13, 0
	global_store_dwordx4 v248, v[50:53], s[14:15]
	s_waitcnt lgkmcnt(2)
	s_add_u32 s14, s12, 0xd000
	s_addc_u32 s15, s13, 0
	global_store_dwordx4 v248, v[54:57], s[14:15]
	s_waitcnt lgkmcnt(1)
	s_add_u32 s14, s12, 0xe000
	s_addc_u32 s15, s13, 0
	global_store_dwordx4 v248, v[58:61], s[14:15]
	s_waitcnt lgkmcnt(0)
	s_add_u32 s14, s12, 0xf000
	s_addc_u32 s15, s13, 0
	global_store_dwordx4 v248, v[62:65], s[14:15]
	s_branch .LBB0_561
